# v45 + partial-sum folds de-serialised: final phase loads all 11 K-slices of two row quarters together (2 round trips per row instead of 44); norm1 fetches slices one ahead into a second register set
# speedup vs baseline: 1.0129x; 1.0034x over previous
; DI void final_phase(PARAMS P, int wave, int lane) {
;     ...
;         const f32x4* xr = (const f32x4*)(X + (size_t)row * D);
;         f32x4 v[4]; float ss = 0.f;
; #pragma unroll
;         for (int j = 0; j < 4; ++j) v[j] = xr[lane + 64 * j];
;         if (row >= MMAIN) { const float* part = (const float*)(P.ws + WS_PART);
; #pragma unroll 1
;             for (int kh = 0; kh < NKSL; ++kh) { const f32x4* pr = (const f32x4*)(part + ((size_t)kh * (MTOT - MMAIN) + (row - MMAIN)) * 1024);
; #pragma unroll
;                 for (int j = 0; j < 4; ++j) v[j] += pr[lane + 64 * j]; } }
.LBB0_936:
	s_ashr_i32 s9, s8, 31
	s_lshl_b64 s[10:11], s[8:9], 12
	v_lshl_add_u64 v[16:17], v[34:35], 0, s[10:11]
	global_load_dwordx4 v[28:31], v[16:17], off
	global_load_dwordx4 v[24:27], v[16:17], off offset:1024
	global_load_dwordx4 v[20:23], v[16:17], off offset:2048
	s_nop 0
	global_load_dwordx4 v[16:19], v[16:17], off offset:3072
	s_cmp_lt_i32 s8, 0x8000
	s_cbranch_scc1 .LBB0_927
	s_add_i32 s12, s8, 0xffff8000
	s_lshl_b64 s[10:11], s[12:13], 12
	v_lshl_add_u64 v[44:45], v[36:37], 0, s[10:11]
	s_mov_b64 s[10:11], 0x300000
	v_mov_b32_e32 v42, v44
	v_mov_b32_e32 v43, v45
	global_load_dwordx4 v[48:51], v[42:43], off
	global_load_dwordx4 v[52:55], v[42:43], off offset:1024
	v_lshl_add_u64 v[42:43], v[42:43], 0, s[10:11]
	global_load_dwordx4 v[56:59], v[42:43], off
	global_load_dwordx4 v[60:63], v[42:43], off offset:1024
	v_lshl_add_u64 v[42:43], v[42:43], 0, s[10:11]
	global_load_dwordx4 v[64:67], v[42:43], off
	global_load_dwordx4 v[68:71], v[42:43], off offset:1024
	v_lshl_add_u64 v[42:43], v[42:43], 0, s[10:11]
	global_load_dwordx4 v[72:75], v[42:43], off
	global_load_dwordx4 v[76:79], v[42:43], off offset:1024
	v_lshl_add_u64 v[42:43], v[42:43], 0, s[10:11]
	global_load_dwordx4 v[80:83], v[42:43], off
	global_load_dwordx4 v[84:87], v[42:43], off offset:1024
	v_lshl_add_u64 v[42:43], v[42:43], 0, s[10:11]
	global_load_dwordx4 v[88:91], v[42:43], off
	global_load_dwordx4 v[92:95], v[42:43], off offset:1024
	v_lshl_add_u64 v[42:43], v[42:43], 0, s[10:11]
	global_load_dwordx4 v[96:99], v[42:43], off
	global_load_dwordx4 v[100:103], v[42:43], off offset:1024
	v_lshl_add_u64 v[42:43], v[42:43], 0, s[10:11]
	global_load_dwordx4 v[104:107], v[42:43], off
	global_load_dwordx4 v[108:111], v[42:43], off offset:1024
	v_lshl_add_u64 v[42:43], v[42:43], 0, s[10:11]
	global_load_dwordx4 v[112:115], v[42:43], off
	global_load_dwordx4 v[116:119], v[42:43], off offset:1024
	v_lshl_add_u64 v[42:43], v[42:43], 0, s[10:11]
	global_load_dwordx4 v[120:123], v[42:43], off
	global_load_dwordx4 v[124:127], v[42:43], off offset:1024
	v_lshl_add_u64 v[42:43], v[42:43], 0, s[10:11]
	global_load_dwordx4 v[128:131], v[42:43], off
	global_load_dwordx4 v[132:135], v[42:43], off offset:1024
	s_waitcnt vmcnt(0)
; DI void final_phase(PARAMS P, int wave, int lane) {
;     ...
;         if (row >= MMAIN) { const float* part = (const float*)(P.ws + WS_PART);
; #pragma unroll 1
;             for (int kh = 0; kh < NKSL; ++kh) { const f32x4* pr = (const f32x4*)(part + ((size_t)kh * (MTOT - MMAIN) + (row - MMAIN)) * 1024);
; #pragma unroll
;                 for (int j = 0; j < 4; ++j) v[j] += pr[lane + 64 * j]; } }
	v_pk_add_f32 v[30:31], v[30:31], v[50:51]
	v_pk_add_f32 v[28:29], v[28:29], v[48:49]
	v_pk_add_f32 v[26:27], v[26:27], v[54:55]
	v_pk_add_f32 v[24:25], v[24:25], v[52:53]
	v_pk_add_f32 v[30:31], v[30:31], v[58:59]
	v_pk_add_f32 v[28:29], v[28:29], v[56:57]
	v_pk_add_f32 v[26:27], v[26:27], v[62:63]
	v_pk_add_f32 v[24:25], v[24:25], v[60:61]
	v_pk_add_f32 v[30:31], v[30:31], v[66:67]
	v_pk_add_f32 v[28:29], v[28:29], v[64:65]
	v_pk_add_f32 v[26:27], v[26:27], v[70:71]
	v_pk_add_f32 v[24:25], v[24:25], v[68:69]
	v_pk_add_f32 v[30:31], v[30:31], v[74:75]
	v_pk_add_f32 v[28:29], v[28:29], v[72:73]
	v_pk_add_f32 v[26:27], v[26:27], v[78:79]
	v_pk_add_f32 v[24:25], v[24:25], v[76:77]
	v_pk_add_f32 v[30:31], v[30:31], v[82:83]
	v_pk_add_f32 v[28:29], v[28:29], v[80:81]
	v_pk_add_f32 v[26:27], v[26:27], v[86:87]
	v_pk_add_f32 v[24:25], v[24:25], v[84:85]
	v_pk_add_f32 v[30:31], v[30:31], v[90:91]
	v_pk_add_f32 v[28:29], v[28:29], v[88:89]
	v_pk_add_f32 v[26:27], v[26:27], v[94:95]
	v_pk_add_f32 v[24:25], v[24:25], v[92:93]
	v_pk_add_f32 v[30:31], v[30:31], v[98:99]
	v_pk_add_f32 v[28:29], v[28:29], v[96:97]
	v_pk_add_f32 v[26:27], v[26:27], v[102:103]
	v_pk_add_f32 v[24:25], v[24:25], v[100:101]
	v_pk_add_f32 v[30:31], v[30:31], v[106:107]
	v_pk_add_f32 v[28:29], v[28:29], v[104:105]
	v_pk_add_f32 v[26:27], v[26:27], v[110:111]
	v_pk_add_f32 v[24:25], v[24:25], v[108:109]
	v_pk_add_f32 v[30:31], v[30:31], v[114:115]
	v_pk_add_f32 v[28:29], v[28:29], v[112:113]
	v_pk_add_f32 v[26:27], v[26:27], v[118:119]
	v_pk_add_f32 v[24:25], v[24:25], v[116:117]
	v_pk_add_f32 v[30:31], v[30:31], v[122:123]
	v_pk_add_f32 v[28:29], v[28:29], v[120:121]
	v_pk_add_f32 v[26:27], v[26:27], v[126:127]
	v_pk_add_f32 v[24:25], v[24:25], v[124:125]
	v_pk_add_f32 v[30:31], v[30:31], v[130:131]
	v_pk_add_f32 v[28:29], v[28:29], v[128:129]
	v_pk_add_f32 v[26:27], v[26:27], v[134:135]
	v_pk_add_f32 v[24:25], v[24:25], v[132:133]
	v_mov_b32_e32 v42, v44
	v_mov_b32_e32 v43, v45
	global_load_dwordx4 v[48:51], v[42:43], off offset:2048
	global_load_dwordx4 v[52:55], v[42:43], off offset:3072
	v_lshl_add_u64 v[42:43], v[42:43], 0, s[10:11]
	global_load_dwordx4 v[56:59], v[42:43], off offset:2048
	global_load_dwordx4 v[60:63], v[42:43], off offset:3072
	v_lshl_add_u64 v[42:43], v[42:43], 0, s[10:11]
	global_load_dwordx4 v[64:67], v[42:43], off offset:2048
	global_load_dwordx4 v[68:71], v[42:43], off offset:3072
	v_lshl_add_u64 v[42:43], v[42:43], 0, s[10:11]
	global_load_dwordx4 v[72:75], v[42:43], off offset:2048
	global_load_dwordx4 v[76:79], v[42:43], off offset:3072
	v_lshl_add_u64 v[42:43], v[42:43], 0, s[10:11]
	global_load_dwordx4 v[80:83], v[42:43], off offset:2048
	global_load_dwordx4 v[84:87], v[42:43], off offset:3072
	v_lshl_add_u64 v[42:43], v[42:43], 0, s[10:11]
	global_load_dwordx4 v[88:91], v[42:43], off offset:2048
	global_load_dwordx4 v[92:95], v[42:43], off offset:3072
	v_lshl_add_u64 v[42:43], v[42:43], 0, s[10:11]
	global_load_dwordx4 v[96:99], v[42:43], off offset:2048
	global_load_dwordx4 v[100:103], v[42:43], off offset:3072
	v_lshl_add_u64 v[42:43], v[42:43], 0, s[10:11]
	global_load_dwordx4 v[104:107], v[42:43], off offset:2048
	global_load_dwordx4 v[108:111], v[42:43], off offset:3072
	v_lshl_add_u64 v[42:43], v[42:43], 0, s[10:11]
	global_load_dwordx4 v[112:115], v[42:43], off offset:2048
	global_load_dwordx4 v[116:119], v[42:43], off offset:3072
	v_lshl_add_u64 v[42:43], v[42:43], 0, s[10:11]
	global_load_dwordx4 v[120:123], v[42:43], off offset:2048
	global_load_dwordx4 v[124:127], v[42:43], off offset:3072
	v_lshl_add_u64 v[42:43], v[42:43], 0, s[10:11]
	global_load_dwordx4 v[128:131], v[42:43], off offset:2048
	global_load_dwordx4 v[132:135], v[42:43], off offset:3072
	s_waitcnt vmcnt(0)
	v_pk_add_f32 v[22:23], v[22:23], v[50:51]
	v_pk_add_f32 v[20:21], v[20:21], v[48:49]
	v_pk_add_f32 v[18:19], v[18:19], v[54:55]
	v_pk_add_f32 v[16:17], v[16:17], v[52:53]
	v_pk_add_f32 v[22:23], v[22:23], v[58:59]
	v_pk_add_f32 v[20:21], v[20:21], v[56:57]
	v_pk_add_f32 v[18:19], v[18:19], v[62:63]
	v_pk_add_f32 v[16:17], v[16:17], v[60:61]
	v_pk_add_f32 v[22:23], v[22:23], v[66:67]
	v_pk_add_f32 v[20:21], v[20:21], v[64:65]
	v_pk_add_f32 v[18:19], v[18:19], v[70:71]
	v_pk_add_f32 v[16:17], v[16:17], v[68:69]
	v_pk_add_f32 v[22:23], v[22:23], v[74:75]
	v_pk_add_f32 v[20:21], v[20:21], v[72:73]
	v_pk_add_f32 v[18:19], v[18:19], v[78:79]
	v_pk_add_f32 v[16:17], v[16:17], v[76:77]
	v_pk_add_f32 v[22:23], v[22:23], v[82:83]
	v_pk_add_f32 v[20:21], v[20:21], v[80:81]
	v_pk_add_f32 v[18:19], v[18:19], v[86:87]
	v_pk_add_f32 v[16:17], v[16:17], v[84:85]
	v_pk_add_f32 v[22:23], v[22:23], v[90:91]
	v_pk_add_f32 v[20:21], v[20:21], v[88:89]
	v_pk_add_f32 v[18:19], v[18:19], v[94:95]
	v_pk_add_f32 v[16:17], v[16:17], v[92:93]
	v_pk_add_f32 v[22:23], v[22:23], v[98:99]
	v_pk_add_f32 v[20:21], v[20:21], v[96:97]
	v_pk_add_f32 v[18:19], v[18:19], v[102:103]
	v_pk_add_f32 v[16:17], v[16:17], v[100:101]
	v_pk_add_f32 v[22:23], v[22:23], v[106:107]
	v_pk_add_f32 v[20:21], v[20:21], v[104:105]
	v_pk_add_f32 v[18:19], v[18:19], v[110:111]
	v_pk_add_f32 v[16:17], v[16:17], v[108:109]
	v_pk_add_f32 v[22:23], v[22:23], v[114:115]
	v_pk_add_f32 v[20:21], v[20:21], v[112:113]
	v_pk_add_f32 v[18:19], v[18:19], v[118:119]
	v_pk_add_f32 v[16:17], v[16:17], v[116:117]
	v_pk_add_f32 v[22:23], v[22:23], v[122:123]
	v_pk_add_f32 v[20:21], v[20:21], v[120:121]
	v_pk_add_f32 v[18:19], v[18:19], v[126:127]
	v_pk_add_f32 v[16:17], v[16:17], v[124:125]
	v_pk_add_f32 v[22:23], v[22:23], v[130:131]
	v_pk_add_f32 v[20:21], v[20:21], v[128:129]
	v_pk_add_f32 v[18:19], v[18:19], v[134:135]
	v_pk_add_f32 v[16:17], v[16:17], v[132:133]
	s_branch .LBB0_927

; template <int RB> DI void norm_rows(float* X, const f32x4 (&gv)[4], bf16_t* XN, const float* wsm, float* SM, int row0, int lane, const float* part) {
;     ...
;         if (part && row >= MMAIN) {
; #pragma unroll 1
;             for (int kh = 0; kh < NKSL; ++kh) { const f32x4* pr = (const f32x4*)(part + ((size_t)kh * (MTOT - MMAIN) + (row - MMAIN)) * 1024);
; #pragma unroll
;                 for (int j = 0; j < 4; ++j) v[r][j] += pr[lane + 64 * j]; }
; #pragma unroll
;             for (int j = 0; j < 4; ++j) ((f32x4*)(X + (size_t)row * D))[lane + 64 * j] = v[r][j];
;         }
; #pragma unroll
;         for (int j = 0; j < 4; ++j) ss += (v[r][j][0] * v[r][j][0] + v[r][j][1] * v[r][j][1]) + (v[r][j][2] * v[r][j][2] + v[r][j][3] * v[r][j][3]);
;         const float rs = rsqrtf(wave_sum(ss) * (1.f / D) + EPS);
.Ln1_x:
	global_load_dwordx4 v[28:31], v[46:47], off
	global_load_dwordx4 v[24:27], v[46:47], off offset:1024
	global_load_dwordx4 v[20:23], v[46:47], off offset:2048
	global_load_dwordx4 v[16:19], v[46:47], off offset:3072
	s_mov_b64 s[10:11], 0x1000
	v_lshl_add_u64 v[178:179], v[46:47], 0, s[10:11]
	s_mov_b64 s[10:11], 0x3000
	v_lshl_add_u64 v[180:181], v[46:47], 0, s[10:11]
	global_load_dwordx4 v[140:143], v[178:179], off
	global_load_dwordx4 v[136:139], v[178:179], off offset:1024
	global_load_dwordx4 v[132:135], v[178:179], off offset:2048
	global_load_dwordx4 v[128:131], v[178:179], off offset:3072
	global_load_dwordx4 v[156:159], v[180:181], off offset:-4096
	global_load_dwordx4 v[152:155], v[180:181], off offset:-3072
	global_load_dwordx4 v[148:151], v[180:181], off offset:-2048
	global_load_dwordx4 v[144:147], v[180:181], off offset:-1024
	global_load_dwordx4 v[172:175], v[180:181], off
	global_load_dwordx4 v[168:171], v[180:181], off offset:1024
	global_load_dwordx4 v[164:167], v[180:181], off offset:2048
	global_load_dwordx4 v[160:163], v[180:181], off offset:3072
	s_cmp_lt_i32 s6, 0x8000
	s_cselect_b64 s[2:3], -1, 0
	s_or_b64 s[2:3], s[8:9], s[2:3]
	s_and_b64 vcc, exec, s[2:3]
	s_cbranch_vccnz .LBB0_948
	s_add_i32 s12, s6, 0xffff8000
	s_lshl_b64 s[2:3], s[12:13], 12
	v_lshl_add_u64 v[184:185], v[38:39], 0, s[2:3]
	s_mov_b64 s[2:3], 0x300000
	global_load_dwordx4 v[112:115], v[184:185], off
	global_load_dwordx4 v[116:119], v[184:185], off offset:1024
	global_load_dwordx4 v[120:123], v[184:185], off offset:2048
	global_load_dwordx4 v[124:127], v[184:185], off offset:3072
	v_lshl_add_u64 v[184:185], v[184:185], 0, s[2:3]
	s_mov_b32 s1, 0
.Lfr_loop0:
	global_load_dwordx4 v[176:179], v[184:185], off
	global_load_dwordx4 v[180:183], v[184:185], off offset:1024
	global_load_dwordx4 v[188:191], v[184:185], off offset:2048
	global_load_dwordx4 v[192:195], v[184:185], off offset:3072
	v_lshl_add_u64 v[184:185], v[184:185], 0, s[2:3]
	s_waitcnt vmcnt(4)
	v_pk_add_f32 v[30:31], v[30:31], v[114:115]
	v_pk_add_f32 v[28:29], v[28:29], v[112:113]
	v_pk_add_f32 v[26:27], v[26:27], v[118:119]
	v_pk_add_f32 v[24:25], v[24:25], v[116:117]
	v_pk_add_f32 v[22:23], v[22:23], v[122:123]
	v_pk_add_f32 v[20:21], v[20:21], v[120:121]
	v_pk_add_f32 v[18:19], v[18:19], v[126:127]
	v_pk_add_f32 v[16:17], v[16:17], v[124:125]
	global_load_dwordx4 v[112:115], v[184:185], off
	global_load_dwordx4 v[116:119], v[184:185], off offset:1024
	global_load_dwordx4 v[120:123], v[184:185], off offset:2048
	global_load_dwordx4 v[124:127], v[184:185], off offset:3072
	v_lshl_add_u64 v[184:185], v[184:185], 0, s[2:3]
	s_waitcnt vmcnt(4)
	v_pk_add_f32 v[30:31], v[30:31], v[178:179]
	v_pk_add_f32 v[28:29], v[28:29], v[176:177]
	v_pk_add_f32 v[26:27], v[26:27], v[182:183]
	v_pk_add_f32 v[24:25], v[24:25], v[180:181]
	v_pk_add_f32 v[22:23], v[22:23], v[190:191]
	v_pk_add_f32 v[20:21], v[20:21], v[188:189]
	v_pk_add_f32 v[18:19], v[18:19], v[194:195]
	v_pk_add_f32 v[16:17], v[16:17], v[192:193]
	s_add_i32 s1, s1, 1
	s_cmp_lt_u32 s1, 5
	s_cbranch_scc1 .Lfr_loop0
	s_waitcnt vmcnt(0)
	v_pk_add_f32 v[30:31], v[30:31], v[114:115]
	v_pk_add_f32 v[28:29], v[28:29], v[112:113]
	v_pk_add_f32 v[26:27], v[26:27], v[118:119]
	v_pk_add_f32 v[24:25], v[24:25], v[116:117]
	v_pk_add_f32 v[22:23], v[22:23], v[122:123]
	v_pk_add_f32 v[20:21], v[20:21], v[120:121]
	v_pk_add_f32 v[18:19], v[18:19], v[126:127]
	v_pk_add_f32 v[16:17], v[16:17], v[124:125]
	global_store_dwordx4 v[46:47], v[28:31], off
	global_store_dwordx4 v[46:47], v[24:27], off offset:1024
	global_store_dwordx4 v[46:47], v[20:23], off offset:2048
	global_store_dwordx4 v[46:47], v[16:19], off offset:3072
.LBB0_948:
	s_waitcnt vmcnt(15)
	v_pk_mul_f32 v[46:47], v[30:31], v[30:31]
	v_pk_mul_f32 v[48:49], v[28:29], v[28:29]
	s_waitcnt vmcnt(13)
	v_mul_f32_e32 v32, v20, v20
	v_pk_mov_b32 v[50:51], v[48:49], v[46:47] op_sel:[1,0]
	v_mov_b32_e32 v49, v47
	v_pk_add_f32 v[46:47], v[50:51], v[48:49]
	v_pk_mul_f32 v[48:49], v[26:27], v[26:27]
	v_pk_mul_f32 v[50:51], v[24:25], v[24:25]
	v_pk_add_f32 v[46:47], v[46:47], v[46:47] op_sel_hi:[0,1]
	v_pk_mov_b32 v[52:53], v[50:51], v[48:49] op_sel:[1,0]
	v_mov_b32_e32 v51, v49
	v_pk_add_f32 v[48:49], v[52:53], v[50:51]
	v_pk_fma_f32 v[50:51], v[20:21], v[20:21], v[32:33] op_sel_hi:[1,1,0]
	v_mul_f32_e32 v32, v22, v22
	v_pk_add_f32 v[48:49], v[48:49], v[48:49] op_sel_hi:[0,1]
	v_pk_fma_f32 v[52:53], v[22:23], v[22:23], v[32:33] op_sel_hi:[1,1,0]
	s_waitcnt vmcnt(12)
; __device__ __forceinline__ unsigned cvt_pk_bf16(float lo, float hi) { const f32x2_cv v = {lo, hi}; const bf16x2_cv b = __builtin_convertvector(v, bf16x2_cv); return __builtin_bit_cast(unsigned, b); }
; template <int RB> DI void norm_rows(float* X, const f32x4 (&gv)[4], bf16_t* XN, const float* wsm, float* SM, int row0, int lane, const float* part) {
;     ...
;         if (part && row >= MMAIN) {
; #pragma unroll 1
;             for (int kh = 0; kh < NKSL; ++kh) { const f32x4* pr = (const f32x4*)(part + ((size_t)kh * (MTOT - MMAIN) + (row - MMAIN)) * 1024);
; #pragma unroll
;                 for (int j = 0; j < 4; ++j) v[r][j] += pr[lane + 64 * j]; }
; #pragma unroll
;             for (int j = 0; j < 4; ++j) ((f32x4*)(X + (size_t)row * D))[lane + 64 * j] = v[r][j];
;     ...
;         const float rs = rsqrtf(wave_sum(ss) * (1.f / D) + EPS);
;         u32x2* o = (u32x2*)(XN + (size_t)row * D);
; #pragma unroll
;         for (int j = 0; j < 4; ++j) { v[r][j] = v[r][j] * rs * gv[j]; u32x2 w; w.x = cvt_pk_bf16(v[r][j][0], v[r][j][1]); w.y = cvt_pk_bf16(v[r][j][2], v[r][j][3]); o[lane + 64 * j] = w; }
	v_mul_f32_e32 v50, v16, v16
	v_mul_f32_e32 v52, v17, v17
	v_mul_f32_e32 v48, v18, v18
	v_mul_f32_e32 v46, v19, v19
	v_pk_add_f32 v[50:51], v[50:51], v[52:53]
	v_pk_add_f32 v[46:47], v[48:49], v[46:47]
	s_lshl_b64 s[16:17], s[6:7], 10
	v_pk_add_f32 v[46:47], v[50:51], v[46:47]
	s_nop 0
	v_add_f32_e32 v32, v46, v47
	s_nop 1
	v_add_f32_dpp v32, v32, v32 quad_perm:[1,0,3,2] row_mask:0xf bank_mask:0xf bound_ctrl:1
	s_nop 1
	v_add_f32_dpp v32, v32, v32 quad_perm:[2,3,0,1] row_mask:0xf bank_mask:0xf bound_ctrl:1
	s_nop 1
	v_add_f32_dpp v32, v32, v32 row_half_mirror row_mask:0xf bank_mask:0xf bound_ctrl:1
	s_nop 1
	v_add_f32_dpp v32, v32, v32 row_mirror row_mask:0xf bank_mask:0xf bound_ctrl:1
	s_nop 0
	v_readlane_b32 s1, v32, 16
	v_readlane_b32 s10, v32, 48
	v_readlane_b32 s2, v32, 0
	v_readlane_b32 s3, v32, 32
	v_mov_b32_e32 v46, s1
	v_mov_b32_e32 v47, s10
	v_pk_add_f32 v[46:47], s[2:3], v[46:47]
	s_nop 0
	v_add_f32_e32 v32, v46, v47
	v_fmamk_f32 v32, v32, 0x3a800000, v229
	v_mul_f32_e32 v43, 0x4b800000, v32
	v_cmp_gt_f32_e32 vcc, s81, v32
	s_nop 1
	v_cndmask_b32_e32 v32, v32, v43, vcc
	v_rsq_f32_e32 v32, v32
	s_nop 0
	v_mul_f32_e32 v43, 0x45800000, v32
	v_cndmask_b32_e32 v32, v32, v43, vcc
	v_pk_mul_f32 v[30:31], v[30:31], v[32:33] op_sel_hi:[1,0]
	v_pk_mul_f32 v[28:29], v[28:29], v[32:33] op_sel_hi:[1,0]
	v_pk_mul_f32 v[46:47], v[2:3], v[30:31]
	v_lshl_add_u64 v[30:31], s[16:17], 1, v[40:41]
	v_pk_mul_f32 v[24:25], v[24:25], v[32:33] op_sel_hi:[1,0]
	v_pk_mul_f32 v[26:27], v[26:27], v[32:33] op_sel_hi:[1,0]
	v_pk_mul_f32 v[20:21], v[20:21], v[32:33] op_sel_hi:[1,0]
	v_pk_mul_f32 v[22:23], v[22:23], v[32:33] op_sel_hi:[1,0]
	v_pk_mul_f32 v[16:17], v[16:17], v[32:33] op_sel_hi:[1,0]
	v_pk_mul_f32 v[18:19], v[18:19], v[32:33] op_sel_hi:[1,0]
	s_or_b32 s16, s6, 1
	v_pk_mul_f32 v[48:49], v[0:1], v[28:29]
	v_pk_mul_f32 v[50:51], v[6:7], v[26:27]
	v_pk_mul_f32 v[52:53], v[4:5], v[24:25]
	v_pk_mul_f32 v[54:55], v[10:11], v[22:23]
	v_pk_mul_f32 v[56:57], v[8:9], v[20:21]
	v_pk_mul_f32 v[58:59], v[14:15], v[18:19]
	v_pk_mul_f32 v[60:61], v[12:13], v[16:17]
	s_ashr_i32 s17, s16, 31
	v_cvt_pk_bf16_f32 v28, v48, v49
	v_cvt_pk_bf16_f32 v29, v46, v47
	v_cvt_pk_bf16_f32 v24, v52, v53
	v_cvt_pk_bf16_f32 v25, v50, v51
	v_cvt_pk_bf16_f32 v20, v56, v57
	v_cvt_pk_bf16_f32 v21, v54, v55
	v_cvt_pk_bf16_f32 v16, v60, v61
	v_cvt_pk_bf16_f32 v17, v58, v59
	s_lshl_b64 s[2:3], s[16:17], 12
	global_store_dwordx2 v[30:31], v[28:29], off
	global_store_dwordx2 v[30:31], v[24:25], off offset:512
	global_store_dwordx2 v[30:31], v[20:21], off offset:1024
	global_store_dwordx2 v[30:31], v[16:17], off offset:1536
	v_lshl_add_u64 v[62:63], v[36:37], 0, s[2:3]
	s_waitcnt vmcnt(12)
	v_mov_b64_e32 v[16:17], v[128:129]
	v_mov_b64_e32 v[18:19], v[130:131]
	v_mov_b64_e32 v[20:21], v[132:133]
	v_mov_b64_e32 v[22:23], v[134:135]
	v_mov_b64_e32 v[24:25], v[136:137]
	v_mov_b64_e32 v[26:27], v[138:139]
	v_mov_b64_e32 v[28:29], v[140:141]
	v_mov_b64_e32 v[30:31], v[142:143]
	s_cmpk_lt_i32 s6, 0x7fff
	s_cselect_b64 s[2:3], -1, 0
	s_or_b64 s[2:3], s[8:9], s[2:3]
	s_and_b64 vcc, exec, s[2:3]
	s_cbranch_vccnz .LBB0_952
	s_add_i32 s12, s6, 0xffff8001
	s_lshl_b64 s[2:3], s[12:13], 12
	v_lshl_add_u64 v[184:185], v[38:39], 0, s[2:3]
	s_mov_b64 s[2:3], 0x300000
	global_load_dwordx4 v[112:115], v[184:185], off
	global_load_dwordx4 v[116:119], v[184:185], off offset:1024
	global_load_dwordx4 v[120:123], v[184:185], off offset:2048
	global_load_dwordx4 v[124:127], v[184:185], off offset:3072
	v_lshl_add_u64 v[184:185], v[184:185], 0, s[2:3]
	s_mov_b32 s1, 0
.Lfr_loop1:
	global_load_dwordx4 v[176:179], v[184:185], off
	global_load_dwordx4 v[180:183], v[184:185], off offset:1024
	global_load_dwordx4 v[188:191], v[184:185], off offset:2048
	global_load_dwordx4 v[192:195], v[184:185], off offset:3072
	v_lshl_add_u64 v[184:185], v[184:185], 0, s[2:3]
	s_waitcnt vmcnt(4)
	v_pk_add_f32 v[30:31], v[30:31], v[114:115]
	v_pk_add_f32 v[28:29], v[28:29], v[112:113]
	v_pk_add_f32 v[26:27], v[26:27], v[118:119]
	v_pk_add_f32 v[24:25], v[24:25], v[116:117]
	v_pk_add_f32 v[22:23], v[22:23], v[122:123]
	v_pk_add_f32 v[20:21], v[20:21], v[120:121]
	v_pk_add_f32 v[18:19], v[18:19], v[126:127]
	v_pk_add_f32 v[16:17], v[16:17], v[124:125]
	global_load_dwordx4 v[112:115], v[184:185], off
	global_load_dwordx4 v[116:119], v[184:185], off offset:1024
	global_load_dwordx4 v[120:123], v[184:185], off offset:2048
	global_load_dwordx4 v[124:127], v[184:185], off offset:3072
	v_lshl_add_u64 v[184:185], v[184:185], 0, s[2:3]
	s_waitcnt vmcnt(4)
	v_pk_add_f32 v[30:31], v[30:31], v[178:179]
	v_pk_add_f32 v[28:29], v[28:29], v[176:177]
	v_pk_add_f32 v[26:27], v[26:27], v[182:183]
	v_pk_add_f32 v[24:25], v[24:25], v[180:181]
	v_pk_add_f32 v[22:23], v[22:23], v[190:191]
	v_pk_add_f32 v[20:21], v[20:21], v[188:189]
	v_pk_add_f32 v[18:19], v[18:19], v[194:195]
	v_pk_add_f32 v[16:17], v[16:17], v[192:193]
	s_add_i32 s1, s1, 1
	s_cmp_lt_u32 s1, 5
	s_cbranch_scc1 .Lfr_loop1
	s_waitcnt vmcnt(0)
	v_pk_add_f32 v[30:31], v[30:31], v[114:115]
	v_pk_add_f32 v[28:29], v[28:29], v[112:113]
	v_pk_add_f32 v[26:27], v[26:27], v[118:119]
	v_pk_add_f32 v[24:25], v[24:25], v[116:117]
	v_pk_add_f32 v[22:23], v[22:23], v[122:123]
	v_pk_add_f32 v[20:21], v[20:21], v[120:121]
	v_pk_add_f32 v[18:19], v[18:19], v[126:127]
	v_pk_add_f32 v[16:17], v[16:17], v[124:125]
	global_store_dwordx4 v[62:63], v[28:31], off
	global_store_dwordx4 v[62:63], v[24:27], off offset:1024
	global_store_dwordx4 v[62:63], v[20:23], off offset:2048
	global_store_dwordx4 v[62:63], v[16:19], off offset:3072
; __device__ __forceinline__ unsigned cvt_pk_bf16(float lo, float hi) { const f32x2_cv v = {lo, hi}; const bf16x2_cv b = __builtin_convertvector(v, bf16x2_cv); return __builtin_bit_cast(unsigned, b); }
; template <int RB> DI void norm_rows(float* X, const f32x4 (&gv)[4], bf16_t* XN, const float* wsm, float* SM, int row0, int lane, const float* part) {
;     ...
;         if (part && row >= MMAIN) {
; #pragma unroll 1
;             for (int kh = 0; kh < NKSL; ++kh) { const f32x4* pr = (const f32x4*)(part + ((size_t)kh * (MTOT - MMAIN) + (row - MMAIN)) * 1024);
; #pragma unroll
;                 for (int j = 0; j < 4; ++j) v[r][j] += pr[lane + 64 * j]; }
; #pragma unroll
;             for (int j = 0; j < 4; ++j) ((f32x4*)(X + (size_t)row * D))[lane + 64 * j] = v[r][j];
;     ...
;         const float rs = rsqrtf(wave_sum(ss) * (1.f / D) + EPS);
;         u32x2* o = (u32x2*)(XN + (size_t)row * D);
; #pragma unroll
;         for (int j = 0; j < 4; ++j) { v[r][j] = v[r][j] * rs * gv[j]; u32x2 w; w.x = cvt_pk_bf16(v[r][j][0], v[r][j][1]); w.y = cvt_pk_bf16(v[r][j][2], v[r][j][3]); o[lane + 64 * j] = w; }
.LBB0_952:
	v_pk_mul_f32 v[62:63], v[30:31], v[30:31]
	v_pk_mul_f32 v[64:65], v[28:29], v[28:29]
	v_mul_f32_e32 v32, v20, v20
	v_pk_mov_b32 v[66:67], v[64:65], v[62:63] op_sel:[1,0]
	v_mov_b32_e32 v65, v63
	v_pk_add_f32 v[62:63], v[66:67], v[64:65]
	v_pk_mul_f32 v[64:65], v[26:27], v[26:27]
	v_pk_mul_f32 v[66:67], v[24:25], v[24:25]
	v_pk_add_f32 v[62:63], v[62:63], v[62:63] op_sel_hi:[0,1]
	v_pk_mov_b32 v[68:69], v[66:67], v[64:65] op_sel:[1,0]
	v_mov_b32_e32 v67, v65
	v_pk_add_f32 v[64:65], v[68:69], v[66:67]
	v_pk_fma_f32 v[66:67], v[20:21], v[20:21], v[32:33] op_sel_hi:[1,1,0]
	v_mul_f32_e32 v32, v22, v22
	v_pk_add_f32 v[64:65], v[64:65], v[64:65] op_sel_hi:[0,1]
	v_pk_fma_f32 v[68:69], v[22:23], v[22:23], v[32:33] op_sel_hi:[1,1,0]
	v_mul_f32_e32 v66, v16, v16
	v_mul_f32_e32 v68, v17, v17
	v_mul_f32_e32 v64, v18, v18
	v_mul_f32_e32 v62, v19, v19
	v_pk_add_f32 v[66:67], v[66:67], v[68:69]
	v_pk_add_f32 v[62:63], v[64:65], v[62:63]
	s_or_b32 s38, s6, 2
	v_pk_add_f32 v[62:63], v[66:67], v[62:63]
	s_lshl_b64 s[20:21], s[16:17], 10
	v_add_f32_e32 v32, v62, v63
	s_ashr_i32 s39, s38, 31
	s_nop 0
	v_add_f32_dpp v32, v32, v32 quad_perm:[1,0,3,2] row_mask:0xf bank_mask:0xf bound_ctrl:1
	s_nop 1
	v_add_f32_dpp v32, v32, v32 quad_perm:[2,3,0,1] row_mask:0xf bank_mask:0xf bound_ctrl:1
	s_nop 1
	v_add_f32_dpp v32, v32, v32 row_half_mirror row_mask:0xf bank_mask:0xf bound_ctrl:1
	s_nop 1
	v_add_f32_dpp v32, v32, v32 row_mirror row_mask:0xf bank_mask:0xf bound_ctrl:1
	s_nop 0
	v_readlane_b32 s1, v32, 16
	v_readlane_b32 s10, v32, 48
	v_readlane_b32 s2, v32, 0
	v_readlane_b32 s3, v32, 32
	v_mov_b32_e32 v62, s1
	v_mov_b32_e32 v63, s10
	v_pk_add_f32 v[62:63], s[2:3], v[62:63]
	s_lshl_b64 s[2:3], s[38:39], 12
	v_add_f32_e32 v32, v62, v63
	v_fmamk_f32 v32, v32, 0x3a800000, v229
	v_mul_f32_e32 v43, 0x4b800000, v32
	v_cmp_gt_f32_e32 vcc, s81, v32
	v_lshl_add_u64 v[78:79], v[36:37], 0, s[2:3]
	s_cmpk_lt_i32 s6, 0x7ffe
	v_cndmask_b32_e32 v32, v32, v43, vcc
	v_rsq_f32_e32 v32, v32
	s_cselect_b64 s[2:3], -1, 0
	s_or_b64 s[2:3], s[8:9], s[2:3]
	v_mul_f32_e32 v43, 0x45800000, v32
	v_cndmask_b32_e32 v32, v32, v43, vcc
	v_pk_mul_f32 v[28:29], v[28:29], v[32:33] op_sel_hi:[1,0]
	v_pk_mul_f32 v[30:31], v[30:31], v[32:33] op_sel_hi:[1,0]
	v_pk_mul_f32 v[24:25], v[24:25], v[32:33] op_sel_hi:[1,0]
	v_pk_mul_f32 v[26:27], v[26:27], v[32:33] op_sel_hi:[1,0]
	v_pk_mul_f32 v[20:21], v[20:21], v[32:33] op_sel_hi:[1,0]
	v_pk_mul_f32 v[22:23], v[22:23], v[32:33] op_sel_hi:[1,0]
	v_pk_mul_f32 v[16:17], v[16:17], v[32:33] op_sel_hi:[1,0]
	v_pk_mul_f32 v[18:19], v[18:19], v[32:33] op_sel_hi:[1,0]
	v_pk_mul_f32 v[62:63], v[2:3], v[30:31]
	v_pk_mul_f32 v[64:65], v[0:1], v[28:29]
	v_pk_mul_f32 v[66:67], v[6:7], v[26:27]
	v_pk_mul_f32 v[68:69], v[4:5], v[24:25]
	v_pk_mul_f32 v[70:71], v[10:11], v[22:23]
	v_pk_mul_f32 v[72:73], v[8:9], v[20:21]
	v_pk_mul_f32 v[74:75], v[14:15], v[18:19]
	v_pk_mul_f32 v[76:77], v[12:13], v[16:17]
	v_cvt_pk_bf16_f32 v28, v64, v65
	v_cvt_pk_bf16_f32 v29, v62, v63
	v_lshl_add_u64 v[30:31], s[20:21], 1, v[40:41]
	v_cvt_pk_bf16_f32 v24, v68, v69
	v_cvt_pk_bf16_f32 v25, v66, v67
	v_cvt_pk_bf16_f32 v20, v72, v73
	v_cvt_pk_bf16_f32 v21, v70, v71
	v_cvt_pk_bf16_f32 v16, v76, v77
	v_cvt_pk_bf16_f32 v17, v74, v75
	global_store_dwordx2 v[30:31], v[28:29], off
	global_store_dwordx2 v[30:31], v[24:25], off offset:512
	global_store_dwordx2 v[30:31], v[20:21], off offset:1024
	global_store_dwordx2 v[30:31], v[16:17], off offset:1536
	s_waitcnt vmcnt(12)
	v_mov_b64_e32 v[16:17], v[144:145]
	v_mov_b64_e32 v[18:19], v[146:147]
	v_mov_b64_e32 v[20:21], v[148:149]
	v_mov_b64_e32 v[22:23], v[150:151]
	v_mov_b64_e32 v[24:25], v[152:153]
	v_mov_b64_e32 v[26:27], v[154:155]
	v_mov_b64_e32 v[28:29], v[156:157]
	v_mov_b64_e32 v[30:31], v[158:159]
	s_and_b64 vcc, exec, s[2:3]
	s_cbranch_vccnz .LBB0_956
	s_add_i32 s12, s6, 0xffff8002
	s_lshl_b64 s[2:3], s[12:13], 12
	v_lshl_add_u64 v[184:185], v[38:39], 0, s[2:3]
	s_mov_b64 s[2:3], 0x300000
	global_load_dwordx4 v[112:115], v[184:185], off
	global_load_dwordx4 v[116:119], v[184:185], off offset:1024
	global_load_dwordx4 v[120:123], v[184:185], off offset:2048
	global_load_dwordx4 v[124:127], v[184:185], off offset:3072
	v_lshl_add_u64 v[184:185], v[184:185], 0, s[2:3]
	s_mov_b32 s1, 0
.Lfr_loop2:
	global_load_dwordx4 v[176:179], v[184:185], off
	global_load_dwordx4 v[180:183], v[184:185], off offset:1024
	global_load_dwordx4 v[188:191], v[184:185], off offset:2048
	global_load_dwordx4 v[192:195], v[184:185], off offset:3072
	v_lshl_add_u64 v[184:185], v[184:185], 0, s[2:3]
	s_waitcnt vmcnt(4)
	v_pk_add_f32 v[30:31], v[30:31], v[114:115]
	v_pk_add_f32 v[28:29], v[28:29], v[112:113]
	v_pk_add_f32 v[26:27], v[26:27], v[118:119]
	v_pk_add_f32 v[24:25], v[24:25], v[116:117]
	v_pk_add_f32 v[22:23], v[22:23], v[122:123]
	v_pk_add_f32 v[20:21], v[20:21], v[120:121]
	v_pk_add_f32 v[18:19], v[18:19], v[126:127]
	v_pk_add_f32 v[16:17], v[16:17], v[124:125]
	global_load_dwordx4 v[112:115], v[184:185], off
	global_load_dwordx4 v[116:119], v[184:185], off offset:1024
	global_load_dwordx4 v[120:123], v[184:185], off offset:2048
	global_load_dwordx4 v[124:127], v[184:185], off offset:3072
	v_lshl_add_u64 v[184:185], v[184:185], 0, s[2:3]
	s_waitcnt vmcnt(4)
	v_pk_add_f32 v[30:31], v[30:31], v[178:179]
	v_pk_add_f32 v[28:29], v[28:29], v[176:177]
	v_pk_add_f32 v[26:27], v[26:27], v[182:183]
	v_pk_add_f32 v[24:25], v[24:25], v[180:181]
	v_pk_add_f32 v[22:23], v[22:23], v[190:191]
	v_pk_add_f32 v[20:21], v[20:21], v[188:189]
	v_pk_add_f32 v[18:19], v[18:19], v[194:195]
	v_pk_add_f32 v[16:17], v[16:17], v[192:193]
	s_add_i32 s1, s1, 1
	s_cmp_lt_u32 s1, 5
	s_cbranch_scc1 .Lfr_loop2
	s_waitcnt vmcnt(0)
	v_pk_add_f32 v[30:31], v[30:31], v[114:115]
	v_pk_add_f32 v[28:29], v[28:29], v[112:113]
	v_pk_add_f32 v[26:27], v[26:27], v[118:119]
	v_pk_add_f32 v[24:25], v[24:25], v[116:117]
	v_pk_add_f32 v[22:23], v[22:23], v[122:123]
	v_pk_add_f32 v[20:21], v[20:21], v[120:121]
	v_pk_add_f32 v[18:19], v[18:19], v[126:127]
	v_pk_add_f32 v[16:17], v[16:17], v[124:125]
	global_store_dwordx4 v[78:79], v[28:31], off
	global_store_dwordx4 v[78:79], v[24:27], off offset:1024
	global_store_dwordx4 v[78:79], v[20:23], off offset:2048
	global_store_dwordx4 v[78:79], v[16:19], off offset:3072
; __device__ __forceinline__ unsigned cvt_pk_bf16(float lo, float hi) { const f32x2_cv v = {lo, hi}; const bf16x2_cv b = __builtin_convertvector(v, bf16x2_cv); return __builtin_bit_cast(unsigned, b); }
; template <int RB> DI void norm_rows(float* X, const f32x4 (&gv)[4], bf16_t* XN, const float* wsm, float* SM, int row0, int lane, const float* part) {
;     ...
;         if (part && row >= MMAIN) {
; #pragma unroll 1
;             for (int kh = 0; kh < NKSL; ++kh) { const f32x4* pr = (const f32x4*)(part + ((size_t)kh * (MTOT - MMAIN) + (row - MMAIN)) * 1024);
; #pragma unroll
;                 for (int j = 0; j < 4; ++j) v[r][j] += pr[lane + 64 * j]; }
; #pragma unroll
;             for (int j = 0; j < 4; ++j) ((f32x4*)(X + (size_t)row * D))[lane + 64 * j] = v[r][j];
;     ...
;         const float rs = rsqrtf(wave_sum(ss) * (1.f / D) + EPS);
;         u32x2* o = (u32x2*)(XN + (size_t)row * D);
; #pragma unroll
;         for (int j = 0; j < 4; ++j) { v[r][j] = v[r][j] * rs * gv[j]; u32x2 w; w.x = cvt_pk_bf16(v[r][j][0], v[r][j][1]); w.y = cvt_pk_bf16(v[r][j][2], v[r][j][3]); o[lane + 64 * j] = w; }
.LBB0_956:
	v_pk_mul_f32 v[78:79], v[30:31], v[30:31]
	v_pk_mul_f32 v[80:81], v[28:29], v[28:29]
	v_mul_f32_e32 v32, v20, v20
	v_pk_mov_b32 v[82:83], v[80:81], v[78:79] op_sel:[1,0]
	v_mov_b32_e32 v81, v79
	v_pk_add_f32 v[78:79], v[82:83], v[80:81]
	v_pk_mul_f32 v[80:81], v[26:27], v[26:27]
	v_pk_mul_f32 v[82:83], v[24:25], v[24:25]
	v_pk_add_f32 v[78:79], v[78:79], v[78:79] op_sel_hi:[0,1]
	v_pk_mov_b32 v[84:85], v[82:83], v[80:81] op_sel:[1,0]
	v_mov_b32_e32 v83, v81
	v_pk_add_f32 v[80:81], v[84:85], v[82:83]
	v_pk_fma_f32 v[82:83], v[20:21], v[20:21], v[32:33] op_sel_hi:[1,1,0]
	v_mul_f32_e32 v32, v22, v22
	v_pk_add_f32 v[80:81], v[80:81], v[80:81] op_sel_hi:[0,1]
	v_pk_fma_f32 v[84:85], v[22:23], v[22:23], v[32:33] op_sel_hi:[1,1,0]
	v_mul_f32_e32 v82, v16, v16
	v_mul_f32_e32 v84, v17, v17
	v_mul_f32_e32 v80, v18, v18
	v_mul_f32_e32 v78, v19, v19
	v_pk_add_f32 v[82:83], v[82:83], v[84:85]
	v_pk_add_f32 v[78:79], v[80:81], v[78:79]
	s_or_b32 s40, s6, 3
	v_pk_add_f32 v[78:79], v[82:83], v[78:79]
	s_lshl_b64 s[20:21], s[38:39], 10
	v_add_f32_e32 v32, v78, v79
	s_ashr_i32 s41, s40, 31
	s_nop 0
	v_add_f32_dpp v32, v32, v32 quad_perm:[1,0,3,2] row_mask:0xf bank_mask:0xf bound_ctrl:1
	s_nop 1
	v_add_f32_dpp v32, v32, v32 quad_perm:[2,3,0,1] row_mask:0xf bank_mask:0xf bound_ctrl:1
	s_nop 1
	v_add_f32_dpp v32, v32, v32 row_half_mirror row_mask:0xf bank_mask:0xf bound_ctrl:1
	s_nop 1
	v_add_f32_dpp v32, v32, v32 row_mirror row_mask:0xf bank_mask:0xf bound_ctrl:1
	s_nop 0
	v_readlane_b32 s1, v32, 16
	v_readlane_b32 s10, v32, 48
	v_readlane_b32 s2, v32, 0
	v_readlane_b32 s3, v32, 32
	v_mov_b32_e32 v78, s1
	v_mov_b32_e32 v79, s10
	v_pk_add_f32 v[78:79], s[2:3], v[78:79]
	s_lshl_b64 s[2:3], s[40:41], 12
	v_add_f32_e32 v32, v78, v79
	v_fmamk_f32 v32, v32, 0x3a800000, v229
	v_mul_f32_e32 v43, 0x4b800000, v32
	v_cmp_gt_f32_e32 vcc, s81, v32
	v_lshl_add_u64 v[94:95], v[36:37], 0, s[2:3]
	s_cmpk_lt_i32 s6, 0x7ffd
	v_cndmask_b32_e32 v32, v32, v43, vcc
	v_rsq_f32_e32 v32, v32
	s_cselect_b64 s[2:3], -1, 0
	s_or_b64 s[2:3], s[8:9], s[2:3]
	v_mul_f32_e32 v43, 0x45800000, v32
	v_cndmask_b32_e32 v32, v32, v43, vcc
	v_pk_mul_f32 v[28:29], v[28:29], v[32:33] op_sel_hi:[1,0]
	v_pk_mul_f32 v[30:31], v[30:31], v[32:33] op_sel_hi:[1,0]
	v_pk_mul_f32 v[24:25], v[24:25], v[32:33] op_sel_hi:[1,0]
	v_pk_mul_f32 v[26:27], v[26:27], v[32:33] op_sel_hi:[1,0]
	v_pk_mul_f32 v[20:21], v[20:21], v[32:33] op_sel_hi:[1,0]
	v_pk_mul_f32 v[22:23], v[22:23], v[32:33] op_sel_hi:[1,0]
	v_pk_mul_f32 v[16:17], v[16:17], v[32:33] op_sel_hi:[1,0]
	v_pk_mul_f32 v[18:19], v[18:19], v[32:33] op_sel_hi:[1,0]
	v_pk_mul_f32 v[78:79], v[2:3], v[30:31]
	v_pk_mul_f32 v[80:81], v[0:1], v[28:29]
	v_pk_mul_f32 v[82:83], v[6:7], v[26:27]
	v_pk_mul_f32 v[84:85], v[4:5], v[24:25]
	v_pk_mul_f32 v[86:87], v[10:11], v[22:23]
	v_pk_mul_f32 v[88:89], v[8:9], v[20:21]
	v_pk_mul_f32 v[90:91], v[14:15], v[18:19]
	v_pk_mul_f32 v[92:93], v[12:13], v[16:17]
	v_cvt_pk_bf16_f32 v28, v80, v81
	v_cvt_pk_bf16_f32 v29, v78, v79
	v_lshl_add_u64 v[30:31], s[20:21], 1, v[40:41]
	v_cvt_pk_bf16_f32 v24, v84, v85
	v_cvt_pk_bf16_f32 v25, v82, v83
	v_cvt_pk_bf16_f32 v20, v88, v89
	v_cvt_pk_bf16_f32 v21, v86, v87
	v_cvt_pk_bf16_f32 v16, v92, v93
	v_cvt_pk_bf16_f32 v17, v90, v91
	global_store_dwordx2 v[30:31], v[28:29], off
	global_store_dwordx2 v[30:31], v[24:25], off offset:512
	global_store_dwordx2 v[30:31], v[20:21], off offset:1024
	global_store_dwordx2 v[30:31], v[16:17], off offset:1536
	s_waitcnt vmcnt(12)
	v_mov_b64_e32 v[16:17], v[160:161]
	v_mov_b64_e32 v[18:19], v[162:163]
	v_mov_b64_e32 v[20:21], v[164:165]
	v_mov_b64_e32 v[22:23], v[166:167]
	v_mov_b64_e32 v[24:25], v[168:169]
	v_mov_b64_e32 v[26:27], v[170:171]
	v_mov_b64_e32 v[28:29], v[172:173]
	v_mov_b64_e32 v[30:31], v[174:175]
	s_and_b64 vcc, exec, s[2:3]
	s_cbranch_vccnz .LBB0_960
	s_add_i32 s12, s6, 0xffff8003
	s_lshl_b64 s[2:3], s[12:13], 12
	v_lshl_add_u64 v[184:185], v[38:39], 0, s[2:3]
	s_mov_b64 s[2:3], 0x300000
	global_load_dwordx4 v[112:115], v[184:185], off
	global_load_dwordx4 v[116:119], v[184:185], off offset:1024
	global_load_dwordx4 v[120:123], v[184:185], off offset:2048
	global_load_dwordx4 v[124:127], v[184:185], off offset:3072
	v_lshl_add_u64 v[184:185], v[184:185], 0, s[2:3]
	s_mov_b32 s1, 0
.Lfr_loop3:
	global_load_dwordx4 v[176:179], v[184:185], off
	global_load_dwordx4 v[180:183], v[184:185], off offset:1024
	global_load_dwordx4 v[188:191], v[184:185], off offset:2048
	global_load_dwordx4 v[192:195], v[184:185], off offset:3072
	v_lshl_add_u64 v[184:185], v[184:185], 0, s[2:3]
	s_waitcnt vmcnt(4)
	v_pk_add_f32 v[30:31], v[30:31], v[114:115]
	v_pk_add_f32 v[28:29], v[28:29], v[112:113]
	v_pk_add_f32 v[26:27], v[26:27], v[118:119]
	v_pk_add_f32 v[24:25], v[24:25], v[116:117]
	v_pk_add_f32 v[22:23], v[22:23], v[122:123]
	v_pk_add_f32 v[20:21], v[20:21], v[120:121]
	v_pk_add_f32 v[18:19], v[18:19], v[126:127]
	v_pk_add_f32 v[16:17], v[16:17], v[124:125]
	global_load_dwordx4 v[112:115], v[184:185], off
	global_load_dwordx4 v[116:119], v[184:185], off offset:1024
	global_load_dwordx4 v[120:123], v[184:185], off offset:2048
	global_load_dwordx4 v[124:127], v[184:185], off offset:3072
	v_lshl_add_u64 v[184:185], v[184:185], 0, s[2:3]
	s_waitcnt vmcnt(4)
	v_pk_add_f32 v[30:31], v[30:31], v[178:179]
	v_pk_add_f32 v[28:29], v[28:29], v[176:177]
	v_pk_add_f32 v[26:27], v[26:27], v[182:183]
	v_pk_add_f32 v[24:25], v[24:25], v[180:181]
	v_pk_add_f32 v[22:23], v[22:23], v[190:191]
	v_pk_add_f32 v[20:21], v[20:21], v[188:189]
	v_pk_add_f32 v[18:19], v[18:19], v[194:195]
	v_pk_add_f32 v[16:17], v[16:17], v[192:193]
	s_add_i32 s1, s1, 1
	s_cmp_lt_u32 s1, 5
	s_cbranch_scc1 .Lfr_loop3
	s_waitcnt vmcnt(0)
	v_pk_add_f32 v[30:31], v[30:31], v[114:115]
	v_pk_add_f32 v[28:29], v[28:29], v[112:113]
	v_pk_add_f32 v[26:27], v[26:27], v[118:119]
	v_pk_add_f32 v[24:25], v[24:25], v[116:117]
	v_pk_add_f32 v[22:23], v[22:23], v[122:123]
	v_pk_add_f32 v[20:21], v[20:21], v[120:121]
	v_pk_add_f32 v[18:19], v[18:19], v[126:127]
	v_pk_add_f32 v[16:17], v[16:17], v[124:125]
	global_store_dwordx4 v[94:95], v[28:31], off
	global_store_dwordx4 v[94:95], v[24:27], off offset:1024
	global_store_dwordx4 v[94:95], v[20:23], off offset:2048
	global_store_dwordx4 v[94:95], v[16:19], off offset:3072
